# loop-edge edit 4: next-block fragment read, P cvt and address SALU hoisted in front of the step barriers (barrier keeps 5 reads in flight)
# baseline (speedup 1.0000x reference)
.Latt_head2:
	s_waitcnt lgkmcnt(4)
	v_mfma_f32_32x32x16_bf16 v[128:143], v[196:199], v[176:179], v[64:79]
	v_add_f32_e32 v6, v96, v97
	v_add_f32_e32 v6, v98, v6
	v_add_f32_e32 v6, v99, v6
	v_add_f32_e32 v10, v100, v6
	ds_read_b128 v[6:9], v0 offset:4608
	s_waitcnt lgkmcnt(4)
	v_mfma_f32_32x32x16_bf16 v[112:127], v[184:187], v[176:179], v[64:79]
	v_add_f32_e32 v10, v101, v10
	v_add_f32_e32 v10, v102, v10
	v_add_f32_e32 v15, v103, v10
	v_cvt_pk_bf16_f32 v181, v98, v99
	s_add_u32 s62, s58, 0xffff0000
	s_addc_u32 s63, s59, -1
	s_and_b32 s12, s67, 3
	s_mulk_i32 s12, 0x3000
	s_add_i32 s64, s12, s78
	s_mov_b32 m0, s64
	s_nop 0
	global_load_lds_dwordx4 v216, s[62:63]
	ds_read_b128 v[10:13], v0 offset:6144
	s_waitcnt lgkmcnt(4)
	v_mfma_f32_32x32x16_bf16 v[128:143], v[188:191], v[168:171], v[128:143]
	v_add_f32_e32 v15, v104, v15
	v_add_f32_e32 v15, v105, v15
	v_add_f32_e32 v15, v106, v15
	v_cvt_pk_bf16_f32 v182, v100, v101
	ds_read_b128 v[96:99], v0 offset:6656
	s_waitcnt lgkmcnt(4)
	v_mfma_f32_32x32x16_bf16 v[112:127], v[192:195], v[168:171], v[112:127]
	v_add_f32_e32 v15, v107, v15
	v_add_f32_e32 v15, v108, v15
	v_add_f32_e32 v15, v109, v15
	v_cvt_pk_bf16_f32 v183, v102, v103
	s_add_u32 s62, s60, 0xfffff000
	s_addc_u32 s63, s61, -1
	s_add_i32 s12, s12, s85
	s_mov_b32 m0, s12
	s_nop 0
	global_load_lds_dwordx4 v216, s[62:63]
	ds_read_b128 v[100:103], v0 offset:8192
	s_waitcnt lgkmcnt(4)
	v_mfma_f32_32x32x16_bf16 v[128:143], v[2:5], v[164:167], v[128:143]
	v_add_f32_e32 v15, v110, v15
	v_add_f32_e32 v15, v111, v15
	v_add_f32_e32 v15, v80, v15
	ds_read_b128 v[2:5], v0 offset:8704
	s_waitcnt lgkmcnt(4)
	v_mfma_f32_32x32x16_bf16 v[112:127], v[6:9], v[164:167], v[112:127]
	v_add_f32_e32 v15, v81, v15
	v_add_f32_e32 v15, v82, v15
	v_add_f32_e32 v15, v83, v15
	v_cvt_pk_bf16_f32 v173, v106, v107
	s_add_u32 s62, s6, 0xffff0000
	s_addc_u32 s63, s7, -1
	s_add_i32 s12, s23, s86
	s_mov_b32 m0, s12
	s_nop 0
	global_load_lds_dwordx4 v216, s[62:63]
	ds_read_b128 v[104:107], v0 offset:10240
	s_waitcnt lgkmcnt(4)
	v_mfma_f32_32x32x16_bf16 v[128:143], v[10:13], v[156:159], v[128:143]
	v_add_f32_e32 v6, v84, v15
	v_add_f32_e32 v6, v85, v6
	v_cvt_pk_bf16_f32 v174, v108, v109
	v_cvt_pk_bf16_f32 v175, v110, v111
	ds_read_b128 v[108:111], v0 offset:10752
	s_waitcnt lgkmcnt(4)
	v_mfma_f32_32x32x16_bf16 v[112:127], v[96:99], v[156:159], v[112:127]
	v_add_f32_e32 v0, v86, v6
	v_add_f32_e32 v0, v87, v0
	v_cvt_pk_bf16_f32 v160, v80, v81
	v_cvt_pk_bf16_f32 v161, v82, v83
	ds_read_b64_tr_b16 v[6:7], v14 offset:49152
	ds_read_b64_tr_b16 v[8:9], v14 offset:49664
	s_waitcnt lgkmcnt(5)
	v_mfma_f32_32x32x16_bf16 v[128:143], v[100:103], v[148:151], v[128:143]
	v_add_f32_e32 v0, v88, v0
	v_add_f32_e32 v0, v89, v0
	v_cvt_pk_bf16_f32 v162, v84, v85
	v_cvt_pk_bf16_f32 v163, v86, v87
	ds_read_b64_tr_b16 v[10:11], v14 offset:53248
	ds_read_b64_tr_b16 v[12:13], v14 offset:53760
	s_waitcnt lgkmcnt(6)
	v_mfma_f32_32x32x16_bf16 v[112:127], v[2:5], v[148:151], v[112:127]
	v_add_f32_e32 v0, v90, v0
	v_add_f32_e32 v0, v91, v0
	v_cvt_pk_bf16_f32 v152, v88, v89
	v_cvt_pk_bf16_f32 v153, v90, v91
	ds_read_b64_tr_b16 v[80:81], v14 offset:50176
	ds_read_b64_tr_b16 v[82:83], v14 offset:50688
	s_waitcnt lgkmcnt(7)
	v_mfma_f32_32x32x16_bf16 v[128:143], v[104:107], v[144:147], v[128:143]
	v_add_f32_e32 v0, v92, v0
	v_add_f32_e32 v0, v93, v0
	v_cvt_pk_bf16_f32 v154, v92, v93
	ds_read_b64_tr_b16 v[2:3], v14 offset:54272
	ds_read_b64_tr_b16 v[4:5], v14 offset:54784
	s_waitcnt lgkmcnt(8)
	v_mfma_f32_32x32x16_bf16 v[112:127], v[108:111], v[144:147], v[112:127]
	v_add_f32_e32 v0, v94, v0
	v_add_f32_e32 v0, v95, v0
	v_cvt_pk_bf16_f32 v155, v94, v95
	s_nop 1
	v_max_f32_e32 v15, v128, v129
	s_add_i32 s12, s67, -2
	s_and_b32 s12, s12, 3
	s_mulk_i32 s12, 0x3000
	s_nop 2
	v_max3_f32 v84, v130, v131, v113
	v_max3_f32 v15, v15, v112, v114
	v_max3_f32 v15, v15, v115, v132
	v_max3_f32 v84, v84, v134, v135
	v_max3_f32 v15, v15, v133, v116
	v_max3_f32 v84, v84, v118, v119
	v_max3_f32 v15, v15, v117, v136
	v_max3_f32 v84, v84, v138, v139
	v_max3_f32 v15, v15, v137, v120
	v_max3_f32 v84, v84, v122, v123
	v_max3_f32 v15, v15, v121, v140
	v_max3_f32 v84, v84, v142, v143
	v_max3_f32 v15, v15, v141, v124
	v_max3_f32 v84, v84, v126, v127
	v_max3_f32 v15, v15, v125, v84
	v_mov_b32_e32 v84, v15
	s_nop 1
	v_permlane32_swap_b32_e32 v15, v84
	v_max_f32_e32 v15, v15, v84
	v_cmp_lt_f32_e32 vcc, s94, v15
	s_cmp_lg_u64 vcc, 0
	v_add_f32_e32 v0, v218, v0
	s_cselect_b64 s[62:63], -1, 0
	s_cbranch_vccnz .LBB0_840

.Latt_rA_ret:
	ds_read_b128 v[188:191], v15 offset:4096
	v_add_u32_e32 v14, s10, v217
	s_waitcnt vmcnt(3) lgkmcnt(5)
	s_barrier
.LBB0_835:
	s_waitcnt lgkmcnt(4)
	v_mfma_f32_32x32x16_bf16 v[96:111], v[2:5], v[176:179], v[64:79]
	v_add_f32_e32 v80, v128, v129
	v_add_f32_e32 v80, v130, v80
	v_add_f32_e32 v80, v131, v80
	v_add_f32_e32 v80, v132, v80
	v_cvt_pk_bf16_f32 v180, v128, v129
	ds_read_b128 v[2:5], v15 offset:4608
	v_add_f32_e32 v80, v133, v80
	v_add_f32_e32 v80, v134, v80
	v_add_f32_e32 v128, v135, v80
	s_waitcnt lgkmcnt(4)
	v_mfma_f32_32x32x16_bf16 v[80:95], v[6:9], v[176:179], v[64:79]
	v_cvt_pk_bf16_f32 v181, v130, v131
	s_add_i32 s10, s22, s78
	s_mov_b32 m0, s10
	s_nop 0
	global_load_lds_dwordx4 v216, s[58:59]
	ds_read_b128 v[6:9], v15 offset:6144
	s_waitcnt lgkmcnt(4)
	v_mfma_f32_32x32x16_bf16 v[96:111], v[10:13], v[168:171], v[96:111]
	v_add_f32_e32 v128, v136, v128
	v_add_f32_e32 v128, v137, v128
	v_add_f32_e32 v128, v138, v128
	v_cvt_pk_bf16_f32 v182, v132, v133
	ds_read_b128 v[10:13], v15 offset:6656
	s_waitcnt lgkmcnt(4)
	v_mfma_f32_32x32x16_bf16 v[80:95], v[184:187], v[168:171], v[80:95]
	v_add_f32_e32 v128, v139, v128
	v_add_f32_e32 v128, v140, v128
	v_add_f32_e32 v132, v141, v128
	v_cvt_pk_bf16_f32 v183, v134, v135
	s_add_i32 s10, s22, s85
	s_mov_b32 m0, s10
	s_nop 0
	global_load_lds_dwordx4 v216, s[60:61]
	ds_read_b128 v[128:131], v15 offset:8192
	s_waitcnt lgkmcnt(4)
	v_mfma_f32_32x32x16_bf16 v[96:111], v[188:191], v[164:167], v[96:111]
	v_add_f32_e32 v132, v142, v132
	v_add_f32_e32 v132, v143, v132
	v_add_f32_e32 v152, v112, v132
	v_cvt_pk_bf16_f32 v172, v136, v137
	ds_read_b128 v[132:135], v15 offset:8704
	s_waitcnt lgkmcnt(4)
	v_mfma_f32_32x32x16_bf16 v[80:95], v[2:5], v[164:167], v[80:95]
	v_add_f32_e32 v136, v113, v152
	v_add_f32_e32 v136, v114, v136
	v_add_f32_e32 v136, v115, v136
	v_cvt_pk_bf16_f32 v173, v138, v139
	s_add_i32 s10, s12, s86
	s_mov_b32 m0, s10
	s_nop 0
	global_load_lds_dwordx4 v216, s[6:7]
	ds_read_b128 v[2:5], v15 offset:10240
	s_waitcnt lgkmcnt(4)
	v_mfma_f32_32x32x16_bf16 v[96:111], v[6:9], v[156:159], v[96:111]
	v_add_f32_e32 v136, v116, v136
	v_add_f32_e32 v152, v117, v136
	v_cvt_pk_bf16_f32 v174, v140, v141
	v_cvt_pk_bf16_f32 v175, v142, v143
	ds_read_b128 v[136:139], v15 offset:10752
	s_waitcnt lgkmcnt(4)
	v_mfma_f32_32x32x16_bf16 v[80:95], v[10:13], v[156:159], v[80:95]
	v_add_f32_e32 v6, v118, v152
	v_add_f32_e32 v6, v119, v6
	v_cvt_pk_bf16_f32 v160, v112, v113
	v_cvt_pk_bf16_f32 v161, v114, v115
	ds_read_b64_tr_b16 v[112:113], v14 offset:49152
	ds_read_b64_tr_b16 v[114:115], v14 offset:49664
	s_waitcnt lgkmcnt(5)
	v_mfma_f32_32x32x16_bf16 v[96:111], v[128:131], v[148:151], v[96:111]
	v_add_f32_e32 v6, v120, v6
	v_add_f32_e32 v6, v121, v6
	v_cvt_pk_bf16_f32 v162, v116, v117
	v_cvt_pk_bf16_f32 v163, v118, v119
	ds_read_b64_tr_b16 v[10:11], v14 offset:53248
	ds_read_b64_tr_b16 v[12:13], v14 offset:53760
	s_waitcnt lgkmcnt(6)
	v_mfma_f32_32x32x16_bf16 v[80:95], v[132:135], v[148:151], v[80:95]
	v_add_f32_e32 v6, v122, v6
	v_add_f32_e32 v15, v123, v6
	v_cvt_pk_bf16_f32 v152, v120, v121
	v_cvt_pk_bf16_f32 v153, v122, v123
	ds_read_b64_tr_b16 v[6:7], v14 offset:50176
	ds_read_b64_tr_b16 v[8:9], v14 offset:50688
	s_waitcnt lgkmcnt(7)
	v_mfma_f32_32x32x16_bf16 v[96:111], v[2:5], v[144:147], v[96:111]
	v_add_f32_e32 v15, v124, v15
	v_add_f32_e32 v15, v125, v15
	v_cvt_pk_bf16_f32 v154, v124, v125
	ds_read_b64_tr_b16 v[2:3], v14 offset:54272
	ds_read_b64_tr_b16 v[4:5], v14 offset:54784
	s_waitcnt lgkmcnt(8)
	v_mfma_f32_32x32x16_bf16 v[80:95], v[136:139], v[144:147], v[80:95]
	v_add_f32_e32 v15, v126, v15
	v_add_f32_e32 v15, v127, v15
	v_cvt_pk_bf16_f32 v155, v126, v127
	s_nop 1
	v_max_f32_e32 v116, v96, v97
	s_add_i32 s10, s67, -1
	s_and_b32 s22, s10, 3
	s_mulk_i32 s22, 0x3000
	s_nop 2
	v_max3_f32 v117, v98, v99, v81
	v_max3_f32 v116, v116, v80, v82
	v_max3_f32 v116, v116, v83, v100
	v_max3_f32 v117, v117, v102, v103
	v_max3_f32 v116, v116, v101, v84
	v_max3_f32 v117, v117, v86, v87
	v_max3_f32 v116, v116, v85, v104
	v_max3_f32 v117, v117, v106, v107
	v_max3_f32 v116, v116, v105, v88
	v_max3_f32 v117, v117, v90, v91
	v_max3_f32 v116, v116, v89, v108
	v_max3_f32 v117, v117, v110, v111
	v_max3_f32 v116, v116, v109, v92
	v_max3_f32 v117, v117, v94, v95
	v_add_f32_e32 v218, v0, v15
	v_max3_f32 v0, v116, v93, v117
	v_mov_b32_e32 v15, v0
	s_nop 1
	v_permlane32_swap_b32_e32 v0, v15
	v_max_f32_e32 v0, v0, v15
	v_cmp_lt_f32_e32 vcc, s94, v0
	s_cmp_lg_u64 vcc, 0
	s_cselect_b64 s[62:63], -1, 0
	s_cbranch_vccnz .LBB0_843

.Latt_rB_ret:
	v_cvt_pk_bf16_f32 v172, v104, v105
	v_cvt_pk_bf16_f32 v180, v96, v97
	s_add_i32 s12, s67, -3
	s_and_b32 s22, s12, 3
	s_mulk_i32 s22, 0x3000
	v_add_u32_e32 v0, s22, v214
	ds_read_b128 v[2:5], v0 offset:4096
	v_add_u32_e32 v14, s101, v217
	s_waitcnt vmcnt(3) lgkmcnt(5)
	s_barrier
	s_branch .Latt_head2
